# compressed-branch edge blocks: 16 serialized masked bias lookups per column group batched into 16 in-flight LDS reads + select
# speedup vs baseline: 1.0031x; 1.0031x over previous
; __device__ __forceinline__ void logits(float (&v)[4][4], const f32x4 (&s)[4], int tq, int kpos0, int kstride, int fq, int H, const float* btab, float farb, bool use_tab, int wl) {
; #pragma unroll
;     for (int f = 0; f < 4; ++f)
; #pragma unroll
;         for (int i = 0; i < 4; ++i) {
;             const int kk = 32 * (f >> 1) + 8 * fq + 4 * (f & 1) + i;
;             const int dist = tq - (kpos0 + kstride * kk);
;             const bool ok = dist >= 0 && dist < wl;
;             const int di = dist < 0 ? 0 : (dist > 128 ? 128 : dist);
;             v[f][i] = ok ? s[f][i] + btab[di * 16 + H] : -1e30f;
;         }
; __device__ __forceinline__ void unitA(unsigned char* lds, PG8_LAS unsigned char* lds3, const Args& a, int b, int g, int T) {
;     ...
;             for (int cg_ = 0; cg_ < 2; ++cg_) {
;                 f32x4 s[4]; float v[4][4];
;                 if (edge) { qk(s, kf, q[cg_], 0.f); logits(v, s, tq[cg_], 16 * 64 * ib + 31, 16, fq, H, btab, farb, true, 1 << 30); }
;                 else { qk(s, kf, q[cg_], farb);
.LBB0_2251:
	s_andn2_b64 vcc, exec, s[16:17]
	s_cbranch_vccnz .LBB0_2285
	s_waitcnt lgkmcnt(7)
	v_mfma_f32_16x16x32_bf16 v[22:25], v[58:61], v[2:5], 0
	s_waitcnt lgkmcnt(5)
	v_mfma_f32_16x16x32_bf16 v[26:29], v[78:81], v[6:9], v[22:25]
	v_mfma_f32_16x16x32_bf16 v[22:25], v[62:65], v[2:5], 0
	s_waitcnt lgkmcnt(3)
	v_mfma_f32_16x16x32_bf16 v[30:33], v[70:73], v[2:5], 0
	s_waitcnt lgkmcnt(2)
	v_mfma_f32_16x16x32_bf16 v[34:37], v[74:77], v[2:5], 0
	v_mfma_f32_16x16x32_bf16 v[22:25], v[66:69], v[6:9], v[22:25]
	s_waitcnt lgkmcnt(1)
	v_mfma_f32_16x16x32_bf16 v[30:33], v[82:85], v[6:9], v[30:33]
	s_waitcnt lgkmcnt(0)
	v_mfma_f32_16x16x32_bf16 v[38:41], v[54:57], v[6:9], v[34:37]
	s_nop 2
	v_add_u32_e32 v250, 0x270, v99
	v_min_u32_e32 v250, 0x80, v250
	v_lshl_add_u32 v232, v250, 6, v177
	ds_read_b32 v232, v232
	v_add_u32_e32 v250, 0x260, v99
	v_min_u32_e32 v250, 0x80, v250
	v_lshl_add_u32 v233, v250, 6, v177
	ds_read_b32 v233, v233
	v_add_u32_e32 v250, 0x250, v99
	v_min_u32_e32 v250, 0x80, v250
	v_lshl_add_u32 v234, v250, 6, v177
	ds_read_b32 v234, v234
	v_add_u32_e32 v250, 0x240, v99
	v_min_u32_e32 v250, 0x80, v250
	v_lshl_add_u32 v235, v250, 6, v177
	ds_read_b32 v235, v235
	v_add_u32_e32 v250, 0x230, v99
	v_min_u32_e32 v250, 0x80, v250
	v_lshl_add_u32 v236, v250, 6, v177
	ds_read_b32 v236, v236
	v_add_u32_e32 v250, 0x220, v99
	v_min_u32_e32 v250, 0x80, v250
	v_lshl_add_u32 v237, v250, 6, v177
	ds_read_b32 v237, v237
	v_add_u32_e32 v250, 0x210, v99
	v_min_u32_e32 v250, 0x80, v250
	v_lshl_add_u32 v238, v250, 6, v177
	ds_read_b32 v238, v238
	v_add_u32_e32 v250, 0x200, v99
	v_min_u32_e32 v250, 0x80, v250
	v_lshl_add_u32 v239, v250, 6, v177
	ds_read_b32 v239, v239
	v_add_u32_e32 v250, 0x70, v99
	v_min_u32_e32 v250, 0x80, v250
	v_lshl_add_u32 v240, v250, 6, v177
	ds_read_b32 v240, v240
	v_add_u32_e32 v250, 0x60, v99
	v_min_u32_e32 v250, 0x80, v250
	v_lshl_add_u32 v241, v250, 6, v177
	ds_read_b32 v241, v241
	v_add_u32_e32 v250, 0x50, v99
	v_min_u32_e32 v250, 0x80, v250
	v_lshl_add_u32 v242, v250, 6, v177
	ds_read_b32 v242, v242
	v_add_u32_e32 v250, 64, v99
	v_min_u32_e32 v250, 0x80, v250
	v_lshl_add_u32 v243, v250, 6, v177
	ds_read_b32 v243, v243
	v_add_u32_e32 v250, 48, v99
	v_min_u32_e32 v250, 0x80, v250
	v_lshl_add_u32 v244, v250, 6, v177
	ds_read_b32 v244, v244
	v_add_u32_e32 v250, 32, v99
	v_min_u32_e32 v250, 0x80, v250
	v_lshl_add_u32 v245, v250, 6, v177
	ds_read_b32 v245, v245
	v_add_u32_e32 v250, 16, v99
	v_min_u32_e32 v250, 0x80, v250
	v_lshl_add_u32 v246, v250, 6, v177
	ds_read_b32 v246, v246
	v_min_u32_e32 v250, 0x80, v99
	v_lshl_add_u32 v247, v250, 6, v177
	ds_read_b32 v247, v247
	v_add_u32_e32 v248, 0x270, v99
	v_cmp_gt_u32_e32 vcc, 2.0, v248
	v_add_u32_e32 v249, 0x260, v99
	v_cmp_gt_u32_e64 s[16:17], 2.0, v249
	s_waitcnt lgkmcnt(15)
	v_add_f32_e32 v34, v26, v232
	v_cndmask_b32_e32 v34, v148, v34, vcc
	v_add_u32_e32 v248, 0x250, v99
	v_cmp_gt_u32_e32 vcc, 2.0, v248
	s_waitcnt lgkmcnt(14)
	v_add_f32_e32 v35, v27, v233
	v_cndmask_b32_e64 v35, v148, v35, s[16:17]
	v_add_u32_e32 v249, 0x240, v99
	v_cmp_gt_u32_e64 s[16:17], 2.0, v249
	s_waitcnt lgkmcnt(13)
	v_add_f32_e32 v36, v28, v234
	v_cndmask_b32_e32 v36, v148, v36, vcc
	v_add_u32_e32 v248, 0x230, v99
	v_cmp_gt_u32_e32 vcc, 2.0, v248
	s_waitcnt lgkmcnt(12)
	v_add_f32_e32 v37, v29, v235
	v_cndmask_b32_e64 v37, v148, v37, s[16:17]
	v_add_u32_e32 v249, 0x220, v99
	v_cmp_gt_u32_e64 s[16:17], 2.0, v249
	s_waitcnt lgkmcnt(11)
	v_add_f32_e32 v26, v22, v236
	v_cndmask_b32_e32 v26, v148, v26, vcc
	v_add_u32_e32 v248, 0x210, v99
	v_cmp_gt_u32_e32 vcc, 2.0, v248
	s_waitcnt lgkmcnt(10)
	v_add_f32_e32 v27, v23, v237
	v_cndmask_b32_e64 v27, v148, v27, s[16:17]
	v_add_u32_e32 v249, 0x200, v99
	v_cmp_gt_u32_e64 s[16:17], 2.0, v249
	s_waitcnt lgkmcnt(9)
	v_add_f32_e32 v28, v24, v238
	v_cndmask_b32_e32 v28, v148, v28, vcc
	v_add_u32_e32 v248, 0x70, v99
	v_cmp_gt_u32_e32 vcc, 2.0, v248
	s_waitcnt lgkmcnt(8)
	v_add_f32_e32 v29, v25, v239
	v_cndmask_b32_e64 v29, v148, v29, s[16:17]
	v_add_u32_e32 v249, 0x60, v99
	v_cmp_gt_u32_e64 s[16:17], 2.0, v249
	s_waitcnt lgkmcnt(7)
	v_add_f32_e32 v22, v30, v240
	v_cndmask_b32_e32 v22, v148, v22, vcc
	v_add_u32_e32 v248, 0x50, v99
	v_cmp_gt_u32_e32 vcc, 2.0, v248
	s_waitcnt lgkmcnt(6)
	v_add_f32_e32 v23, v31, v241
	v_cndmask_b32_e64 v23, v148, v23, s[16:17]
	v_add_u32_e32 v249, 64, v99
	v_cmp_gt_u32_e64 s[16:17], 2.0, v249
	s_waitcnt lgkmcnt(5)
	v_add_f32_e32 v24, v32, v242
	v_cndmask_b32_e32 v24, v148, v24, vcc
	v_add_u32_e32 v248, 48, v99
	v_cmp_gt_u32_e32 vcc, 2.0, v248
	s_waitcnt lgkmcnt(4)
	v_add_f32_e32 v25, v33, v243
	v_cndmask_b32_e64 v25, v148, v25, s[16:17]
	v_add_u32_e32 v249, 32, v99
	v_cmp_gt_u32_e64 s[16:17], 2.0, v249
	s_waitcnt lgkmcnt(3)
	v_add_f32_e32 v30, v38, v244
	v_cndmask_b32_e32 v30, v148, v30, vcc
	v_add_u32_e32 v248, 16, v99
	v_cmp_gt_u32_e32 vcc, 2.0, v248
	s_waitcnt lgkmcnt(2)
	v_add_f32_e32 v31, v39, v245
	v_cndmask_b32_e64 v31, v148, v31, s[16:17]
	v_cmp_gt_u32_e64 s[16:17], 2.0, v99
	s_waitcnt lgkmcnt(1)
	v_add_f32_e32 v32, v40, v246
	v_cndmask_b32_e32 v32, v148, v32, vcc
	s_waitcnt lgkmcnt(0)
	v_add_f32_e32 v33, v41, v247
	v_cndmask_b32_e64 v33, v148, v33, s[16:17]

; __device__ __forceinline__ void logits(float (&v)[4][4], const f32x4 (&s)[4], int tq, int kpos0, int kstride, int fq, int H, const float* btab, float farb, bool use_tab, int wl) {
; #pragma unroll
;     for (int f = 0; f < 4; ++f)
; #pragma unroll
;         for (int i = 0; i < 4; ++i) {
;             const int kk = 32 * (f >> 1) + 8 * fq + 4 * (f & 1) + i;
;             const int dist = tq - (kpos0 + kstride * kk);
;             const bool ok = dist >= 0 && dist < wl;
;             const int di = dist < 0 ? 0 : (dist > 128 ? 128 : dist);
;             v[f][i] = ok ? s[f][i] + btab[di * 16 + H] : -1e30f;
;         }
; __device__ __forceinline__ void unitA(unsigned char* lds, PG8_LAS unsigned char* lds3, const Args& a, int b, int g, int T) {
;     ...
;             for (int cg_ = 0; cg_ < 2; ++cg_) {
;                 f32x4 s[4]; float v[4][4];
;                 if (edge) { qk(s, kf, q[cg_], 0.f); logits(v, s, tq[cg_], 16 * 64 * ib + 31, 16, fq, H, btab, farb, true, 1 << 30); }
;                 else { qk(s, kf, q[cg_], farb);
.LBB0_2287:
	s_andn2_b64 vcc, exec, s[14:15]
	s_cbranch_vccnz .LBB0_2321
	s_waitcnt lgkmcnt(7)
	v_mfma_f32_16x16x32_bf16 v[38:41], v[58:61], v[10:13], 0
	s_waitcnt lgkmcnt(5)
	v_mfma_f32_16x16x32_bf16 v[44:47], v[78:81], v[14:17], v[38:41]
	v_mfma_f32_16x16x32_bf16 v[38:41], v[62:65], v[10:13], 0
	s_waitcnt lgkmcnt(4)
	v_mfma_f32_16x16x32_bf16 v[58:61], v[66:69], v[14:17], v[38:41]
	s_waitcnt lgkmcnt(3)
	v_mfma_f32_16x16x32_bf16 v[38:41], v[70:73], v[10:13], 0
	s_waitcnt lgkmcnt(2)
	v_mfma_f32_16x16x32_bf16 v[62:65], v[74:77], v[10:13], 0
	s_waitcnt lgkmcnt(1)
	v_mfma_f32_16x16x32_bf16 v[40:43], v[82:85], v[14:17], v[38:41]
	s_waitcnt lgkmcnt(0)
	v_mfma_f32_16x16x32_bf16 v[54:57], v[54:57], v[14:17], v[62:65]
	s_nop 1
	v_add_u32_e32 v250, 0x274, v99
	v_min_u32_e32 v250, 0x80, v250
	v_lshl_add_u32 v232, v250, 6, v177
	ds_read_b32 v232, v232
	v_add_u32_e32 v250, 0x264, v99
	v_min_u32_e32 v250, 0x80, v250
	v_lshl_add_u32 v233, v250, 6, v177
	ds_read_b32 v233, v233
	v_add_u32_e32 v250, 0x254, v99
	v_min_u32_e32 v250, 0x80, v250
	v_lshl_add_u32 v234, v250, 6, v177
	ds_read_b32 v234, v234
	v_add_u32_e32 v250, 0x244, v99
	v_min_u32_e32 v250, 0x80, v250
	v_lshl_add_u32 v235, v250, 6, v177
	ds_read_b32 v235, v235
	v_add_u32_e32 v250, 0x234, v99
	v_min_u32_e32 v250, 0x80, v250
	v_lshl_add_u32 v236, v250, 6, v177
	ds_read_b32 v236, v236
	v_add_u32_e32 v250, 0x224, v99
	v_min_u32_e32 v250, 0x80, v250
	v_lshl_add_u32 v237, v250, 6, v177
	ds_read_b32 v237, v237
	v_add_u32_e32 v250, 0x214, v99
	v_min_u32_e32 v250, 0x80, v250
	v_lshl_add_u32 v238, v250, 6, v177
	ds_read_b32 v238, v238
	v_add_u32_e32 v250, 0x204, v99
	v_min_u32_e32 v250, 0x80, v250
	v_lshl_add_u32 v239, v250, 6, v177
	ds_read_b32 v239, v239
	v_add_u32_e32 v250, 0x74, v99
	v_min_u32_e32 v250, 0x80, v250
	v_lshl_add_u32 v240, v250, 6, v177
	ds_read_b32 v240, v240
	v_add_u32_e32 v250, 0x64, v99
	v_min_u32_e32 v250, 0x80, v250
	v_lshl_add_u32 v241, v250, 6, v177
	ds_read_b32 v241, v241
	v_add_u32_e32 v250, 0x54, v99
	v_min_u32_e32 v250, 0x80, v250
	v_lshl_add_u32 v242, v250, 6, v177
	ds_read_b32 v242, v242
	v_add_u32_e32 v250, 0x44, v99
	v_min_u32_e32 v250, 0x80, v250
	v_lshl_add_u32 v243, v250, 6, v177
	ds_read_b32 v243, v243
	v_add_u32_e32 v250, 52, v99
	v_min_u32_e32 v250, 0x80, v250
	v_lshl_add_u32 v244, v250, 6, v177
	ds_read_b32 v244, v244
	v_add_u32_e32 v250, 36, v99
	v_min_u32_e32 v250, 0x80, v250
	v_lshl_add_u32 v245, v250, 6, v177
	ds_read_b32 v245, v245
	v_add_u32_e32 v250, 20, v99
	v_min_u32_e32 v250, 0x80, v250
	v_lshl_add_u32 v246, v250, 6, v177
	ds_read_b32 v246, v246
	v_add_u32_e32 v250, 4, v99
	v_min_u32_e32 v250, 0x80, v250
	v_lshl_add_u32 v247, v250, 6, v177
	ds_read_b32 v247, v247
	v_add_u32_e32 v248, 0x274, v99
	v_cmp_gt_u32_e32 vcc, 2.0, v248
	v_add_u32_e32 v249, 0x264, v99
	v_cmp_gt_u32_e64 s[14:15], 2.0, v249
	s_waitcnt lgkmcnt(15)
	v_add_f32_e32 v50, v44, v232
	v_cndmask_b32_e32 v50, v148, v50, vcc
	v_add_u32_e32 v248, 0x254, v99
	v_cmp_gt_u32_e32 vcc, 2.0, v248
	s_waitcnt lgkmcnt(14)
	v_add_f32_e32 v51, v45, v233
	v_cndmask_b32_e64 v51, v148, v51, s[14:15]
	v_add_u32_e32 v249, 0x244, v99
	v_cmp_gt_u32_e64 s[14:15], 2.0, v249
	s_waitcnt lgkmcnt(13)
	v_add_f32_e32 v52, v46, v234
	v_cndmask_b32_e32 v52, v148, v52, vcc
	v_add_u32_e32 v248, 0x234, v99
	v_cmp_gt_u32_e32 vcc, 2.0, v248
	s_waitcnt lgkmcnt(12)
	v_add_f32_e32 v53, v47, v235
	v_cndmask_b32_e64 v53, v148, v53, s[14:15]
	v_add_u32_e32 v249, 0x224, v99
	v_cmp_gt_u32_e64 s[14:15], 2.0, v249
	s_waitcnt lgkmcnt(11)
	v_add_f32_e32 v46, v58, v236
	v_cndmask_b32_e32 v46, v148, v46, vcc
	v_add_u32_e32 v248, 0x214, v99
	v_cmp_gt_u32_e32 vcc, 2.0, v248
	s_waitcnt lgkmcnt(10)
	v_add_f32_e32 v47, v59, v237
	v_cndmask_b32_e64 v47, v148, v47, s[14:15]
	v_add_u32_e32 v249, 0x204, v99
	v_cmp_gt_u32_e64 s[14:15], 2.0, v249
	s_waitcnt lgkmcnt(9)
	v_add_f32_e32 v48, v60, v238
	v_cndmask_b32_e32 v48, v148, v48, vcc
	v_add_u32_e32 v248, 0x74, v99
	v_cmp_gt_u32_e32 vcc, 2.0, v248
	s_waitcnt lgkmcnt(8)
	v_add_f32_e32 v49, v61, v239
	v_cndmask_b32_e64 v49, v148, v49, s[14:15]
	v_add_u32_e32 v249, 0x64, v99
	v_cmp_gt_u32_e64 s[14:15], 2.0, v249
	s_waitcnt lgkmcnt(7)
	v_add_f32_e32 v38, v40, v240
	v_cndmask_b32_e32 v38, v148, v38, vcc
	v_add_u32_e32 v248, 0x54, v99
	v_cmp_gt_u32_e32 vcc, 2.0, v248
	s_waitcnt lgkmcnt(6)
	v_add_f32_e32 v39, v41, v241
	v_cndmask_b32_e64 v39, v148, v39, s[14:15]
	v_add_u32_e32 v249, 0x44, v99
	v_cmp_gt_u32_e64 s[14:15], 2.0, v249
	s_waitcnt lgkmcnt(5)
	v_add_f32_e32 v40, v42, v242
	v_cndmask_b32_e32 v40, v148, v40, vcc
	v_add_u32_e32 v248, 52, v99
	v_cmp_gt_u32_e32 vcc, 2.0, v248
	s_waitcnt lgkmcnt(4)
	v_add_f32_e32 v41, v43, v243
	v_cndmask_b32_e64 v41, v148, v41, s[14:15]
	v_add_u32_e32 v249, 36, v99
	v_cmp_gt_u32_e64 s[14:15], 2.0, v249
	s_waitcnt lgkmcnt(3)
	v_add_f32_e32 v42, v54, v244
	v_cndmask_b32_e32 v42, v148, v42, vcc
	v_add_u32_e32 v248, 20, v99
	v_cmp_gt_u32_e32 vcc, 2.0, v248
	s_waitcnt lgkmcnt(2)
	v_add_f32_e32 v43, v55, v245
	v_cndmask_b32_e64 v43, v148, v43, s[14:15]
	v_add_u32_e32 v249, 4, v99
	v_cmp_gt_u32_e64 s[14:15], 2.0, v249
	s_waitcnt lgkmcnt(1)
	v_add_f32_e32 v44, v56, v246
	v_cndmask_b32_e32 v44, v148, v44, vcc
	s_waitcnt lgkmcnt(0)
	v_add_f32_e32 v45, v57, v247
	v_cndmask_b32_e64 v45, v148, v45, s[14:15]

; __device__ __forceinline__ void logits(float (&v)[4][4], const f32x4 (&s)[4], int tq, int kpos0, int kstride, int fq, int H, const float* btab, float farb, bool use_tab, int wl) {
; #pragma unroll
;     for (int f = 0; f < 4; ++f)
; #pragma unroll
;         for (int i = 0; i < 4; ++i) {
;             const int kk = 32 * (f >> 1) + 8 * fq + 4 * (f & 1) + i;
;             const int dist = tq - (kpos0 + kstride * kk);
;             const bool ok = dist >= 0 && dist < wl;
;             const int di = dist < 0 ? 0 : (dist > 128 ? 128 : dist);
;             v[f][i] = ok ? s[f][i] + btab[di * 16 + H] : -1e30f;
;         }
; __device__ __forceinline__ void unitA(unsigned char* lds, PG8_LAS unsigned char* lds3, const Args& a, int b, int g, int T) {
;     ...
;             for (int cg_ = 0; cg_ < 2; ++cg_) {
;                 f32x4 s[4]; float v[4][4];
;                 if (edge) { qk(s, kf, q[cg_], 0.f); logits(v, s, tq[cg_], 16 * 64 * ib + 31, 16, fq, H, btab, farb, true, 1 << 30);
; #pragma unroll
;                     for (int f = 0; f < 4; ++f)
; #pragma unroll
;                         for (int i = 0; i < 4; ++i) v[f][i] -= moff[cg_]; }
.LBB0_2342:
	s_andn2_b64 vcc, exec, s[12:13]
	s_cbranch_vccnz .LBB0_2376
	s_waitcnt lgkmcnt(7)
	v_mfma_f32_16x16x32_bf16 v[92:95], v[64:67], v[2:5], 0
	s_waitcnt lgkmcnt(5)
	v_mfma_f32_16x16x32_bf16 v[104:107], v[84:87], v[6:9], v[92:95]
	v_mfma_f32_16x16x32_bf16 v[92:95], v[68:71], v[2:5], 0
	s_waitcnt lgkmcnt(4)
	v_mfma_f32_16x16x32_bf16 v[100:103], v[72:75], v[6:9], v[92:95]
	s_waitcnt lgkmcnt(3)
	v_mfma_f32_16x16x32_bf16 v[92:95], v[76:79], v[2:5], 0
	s_waitcnt lgkmcnt(1)
	v_mfma_f32_16x16x32_bf16 v[96:99], v[88:91], v[6:9], v[92:95]
	v_mfma_f32_16x16x32_bf16 v[92:95], v[80:83], v[2:5], 0
	s_waitcnt lgkmcnt(0)
	v_mfma_f32_16x16x32_bf16 v[92:95], v[60:63], v[6:9], v[92:95]
	v_add_u32_e32 v250, 0x270, v19
	v_min_u32_e32 v250, 0x80, v250
	v_lshl_add_u32 v232, v250, 6, v177
	ds_read_b32 v232, v232
	v_add_u32_e32 v250, 0x260, v19
	v_min_u32_e32 v250, 0x80, v250
	v_lshl_add_u32 v233, v250, 6, v177
	ds_read_b32 v233, v233
	v_add_u32_e32 v250, 0x250, v19
	v_min_u32_e32 v250, 0x80, v250
	v_lshl_add_u32 v234, v250, 6, v177
	ds_read_b32 v234, v234
	v_add_u32_e32 v250, 0x240, v19
	v_min_u32_e32 v250, 0x80, v250
	v_lshl_add_u32 v235, v250, 6, v177
	ds_read_b32 v235, v235
	v_add_u32_e32 v250, 0x230, v19
	v_min_u32_e32 v250, 0x80, v250
	v_lshl_add_u32 v236, v250, 6, v177
	ds_read_b32 v236, v236
	v_add_u32_e32 v250, 0x220, v19
	v_min_u32_e32 v250, 0x80, v250
	v_lshl_add_u32 v237, v250, 6, v177
	ds_read_b32 v237, v237
	v_add_u32_e32 v250, 0x210, v19
	v_min_u32_e32 v250, 0x80, v250
	v_lshl_add_u32 v238, v250, 6, v177
	ds_read_b32 v238, v238
	v_add_u32_e32 v250, 0x200, v19
	v_min_u32_e32 v250, 0x80, v250
	v_lshl_add_u32 v239, v250, 6, v177
	ds_read_b32 v239, v239
	v_add_u32_e32 v250, 0x70, v19
	v_min_u32_e32 v250, 0x80, v250
	v_lshl_add_u32 v240, v250, 6, v177
	ds_read_b32 v240, v240
	v_add_u32_e32 v250, 0x60, v19
	v_min_u32_e32 v250, 0x80, v250
	v_lshl_add_u32 v241, v250, 6, v177
	ds_read_b32 v241, v241
	v_add_u32_e32 v250, 0x50, v19
	v_min_u32_e32 v250, 0x80, v250
	v_lshl_add_u32 v242, v250, 6, v177
	ds_read_b32 v242, v242
	v_add_u32_e32 v250, 64, v19
	v_min_u32_e32 v250, 0x80, v250
	v_lshl_add_u32 v243, v250, 6, v177
	ds_read_b32 v243, v243
	v_add_u32_e32 v250, 48, v19
	v_min_u32_e32 v250, 0x80, v250
	v_lshl_add_u32 v244, v250, 6, v177
	ds_read_b32 v244, v244
	v_add_u32_e32 v250, 32, v19
	v_min_u32_e32 v250, 0x80, v250
	v_lshl_add_u32 v245, v250, 6, v177
	ds_read_b32 v245, v245
	v_add_u32_e32 v250, 16, v19
	v_min_u32_e32 v250, 0x80, v250
	v_lshl_add_u32 v246, v250, 6, v177
	ds_read_b32 v246, v246
	v_min_u32_e32 v250, 0x80, v19
	v_lshl_add_u32 v247, v250, 6, v177
	ds_read_b32 v247, v247
	v_add_u32_e32 v248, 0x270, v19
	v_cmp_gt_u32_e32 vcc, 2.0, v248
	v_add_u32_e32 v249, 0x260, v19
	v_cmp_gt_u32_e64 s[12:13], 2.0, v249
	s_waitcnt lgkmcnt(15)
	v_add_f32_e32 v116, v104, v232
	v_cndmask_b32_e32 v116, v148, v116, vcc
	v_add_u32_e32 v248, 0x250, v19
	v_cmp_gt_u32_e32 vcc, 2.0, v248
	s_waitcnt lgkmcnt(14)
	v_add_f32_e32 v117, v105, v233
	v_cndmask_b32_e64 v117, v148, v117, s[12:13]
	v_add_u32_e32 v249, 0x240, v19
	v_cmp_gt_u32_e64 s[12:13], 2.0, v249
	s_waitcnt lgkmcnt(13)
	v_add_f32_e32 v118, v106, v234
	v_cndmask_b32_e32 v118, v148, v118, vcc
	v_add_u32_e32 v248, 0x230, v19
	v_cmp_gt_u32_e32 vcc, 2.0, v248
	s_waitcnt lgkmcnt(12)
	v_add_f32_e32 v119, v107, v235
	v_cndmask_b32_e64 v119, v148, v119, s[12:13]
	v_add_u32_e32 v249, 0x220, v19
	v_cmp_gt_u32_e64 s[12:13], 2.0, v249
	s_waitcnt lgkmcnt(11)
	v_add_f32_e32 v120, v100, v236
	v_cndmask_b32_e32 v120, v148, v120, vcc
	v_add_u32_e32 v248, 0x210, v19
	v_cmp_gt_u32_e32 vcc, 2.0, v248
	s_waitcnt lgkmcnt(10)
	v_add_f32_e32 v121, v101, v237
	v_cndmask_b32_e64 v121, v148, v121, s[12:13]
	v_add_u32_e32 v249, 0x200, v19
	v_cmp_gt_u32_e64 s[12:13], 2.0, v249
	s_waitcnt lgkmcnt(9)
	v_add_f32_e32 v122, v102, v238
	v_cndmask_b32_e32 v122, v148, v122, vcc
	v_add_u32_e32 v248, 0x70, v19
	v_cmp_gt_u32_e32 vcc, 2.0, v248
	s_waitcnt lgkmcnt(8)
	v_add_f32_e32 v123, v103, v239
	v_cndmask_b32_e64 v123, v148, v123, s[12:13]
	v_add_u32_e32 v249, 0x60, v19
	v_cmp_gt_u32_e64 s[12:13], 2.0, v249
	s_waitcnt lgkmcnt(7)
	v_add_f32_e32 v124, v96, v240
	v_cndmask_b32_e32 v124, v148, v124, vcc
	v_add_u32_e32 v248, 0x50, v19
	v_cmp_gt_u32_e32 vcc, 2.0, v248
	s_waitcnt lgkmcnt(6)
	v_add_f32_e32 v125, v97, v241
	v_cndmask_b32_e64 v125, v148, v125, s[12:13]
	v_add_u32_e32 v249, 64, v19
	v_cmp_gt_u32_e64 s[12:13], 2.0, v249
	s_waitcnt lgkmcnt(5)
	v_add_f32_e32 v126, v98, v242
	v_cndmask_b32_e32 v126, v148, v126, vcc
	v_add_u32_e32 v248, 48, v19
	v_cmp_gt_u32_e32 vcc, 2.0, v248
	s_waitcnt lgkmcnt(4)
	v_add_f32_e32 v127, v99, v243
	v_cndmask_b32_e64 v127, v148, v127, s[12:13]
	v_add_u32_e32 v249, 32, v19
	v_cmp_gt_u32_e64 s[12:13], 2.0, v249
	s_waitcnt lgkmcnt(3)
	v_add_f32_e32 v128, v92, v244
	v_cndmask_b32_e32 v128, v148, v128, vcc
	v_add_u32_e32 v248, 16, v19
	v_cmp_gt_u32_e32 vcc, 2.0, v248
	s_waitcnt lgkmcnt(2)
	v_add_f32_e32 v129, v93, v245
	v_cndmask_b32_e64 v129, v148, v129, s[12:13]
	v_cmp_gt_u32_e64 s[12:13], 2.0, v19
	s_waitcnt lgkmcnt(1)
	v_add_f32_e32 v130, v94, v246
	v_cndmask_b32_e32 v130, v148, v130, vcc
	s_waitcnt lgkmcnt(0)
	v_add_f32_e32 v131, v95, v247
	v_cndmask_b32_e64 v131, v148, v131, s[12:13]
	v_pk_add_f32 v[104:105], v[116:117], v[112:113] neg_lo:[0,1] neg_hi:[0,1]
	v_pk_add_f32 v[106:107], v[118:119], v[112:113] neg_lo:[0,1] neg_hi:[0,1]
	v_pk_add_f32 v[100:101], v[120:121], v[112:113] neg_lo:[0,1] neg_hi:[0,1]
	v_pk_add_f32 v[102:103], v[122:123], v[112:113] neg_lo:[0,1] neg_hi:[0,1]
	v_pk_add_f32 v[96:97], v[124:125], v[112:113] neg_lo:[0,1] neg_hi:[0,1]
	v_pk_add_f32 v[98:99], v[126:127], v[112:113] neg_lo:[0,1] neg_hi:[0,1]
	v_pk_add_f32 v[92:93], v[128:129], v[112:113] neg_lo:[0,1] neg_hi:[0,1]
	v_pk_add_f32 v[94:95], v[130:131], v[112:113] neg_lo:[0,1] neg_hi:[0,1]

; __device__ __forceinline__ void logits(float (&v)[4][4], const f32x4 (&s)[4], int tq, int kpos0, int kstride, int fq, int H, const float* btab, float farb, bool use_tab, int wl) {
; #pragma unroll
;     for (int f = 0; f < 4; ++f)
; #pragma unroll
;         for (int i = 0; i < 4; ++i) {
;             const int kk = 32 * (f >> 1) + 8 * fq + 4 * (f & 1) + i;
;             const int dist = tq - (kpos0 + kstride * kk);
;             const bool ok = dist >= 0 && dist < wl;
;             const int di = dist < 0 ? 0 : (dist > 128 ? 128 : dist);
;             v[f][i] = ok ? s[f][i] + btab[di * 16 + H] : -1e30f;
;         }
; __device__ __forceinline__ void unitA(unsigned char* lds, PG8_LAS unsigned char* lds3, const Args& a, int b, int g, int T) {
;     ...
;             for (int cg_ = 0; cg_ < 2; ++cg_) {
;                 f32x4 s[4]; float v[4][4];
;                 if (edge) { qk(s, kf, q[cg_], 0.f); logits(v, s, tq[cg_], 16 * 64 * ib + 31, 16, fq, H, btab, farb, true, 1 << 30);
; #pragma unroll
;                     for (int f = 0; f < 4; ++f)
; #pragma unroll
;                         for (int i = 0; i < 4; ++i) v[f][i] -= moff[cg_]; }
.LBB0_2386:
	s_andn2_b64 vcc, exec, s[12:13]
	s_cbranch_vccnz .LBB0_2420
	v_mfma_f32_16x16x32_bf16 v[64:67], v[64:67], v[10:13], 0
	v_mfma_f32_16x16x32_bf16 v[84:87], v[84:87], v[14:17], v[64:67]
	v_mfma_f32_16x16x32_bf16 v[64:67], v[68:71], v[10:13], 0
	v_mfma_f32_16x16x32_bf16 v[68:71], v[72:75], v[14:17], v[64:67]
	v_mfma_f32_16x16x32_bf16 v[64:67], v[76:79], v[10:13], 0
	v_mfma_f32_16x16x32_bf16 v[76:79], v[80:83], v[10:13], 0
	v_mfma_f32_16x16x32_bf16 v[64:67], v[88:91], v[14:17], v[64:67]
	v_mfma_f32_16x16x32_bf16 v[60:63], v[60:63], v[14:17], v[76:79]
	v_add_u32_e32 v250, 0x274, v19
	v_min_u32_e32 v250, 0x80, v250
	v_lshl_add_u32 v232, v250, 6, v177
	ds_read_b32 v232, v232
	v_add_u32_e32 v250, 0x264, v19
	v_min_u32_e32 v250, 0x80, v250
	v_lshl_add_u32 v233, v250, 6, v177
	ds_read_b32 v233, v233
	v_add_u32_e32 v250, 0x254, v19
	v_min_u32_e32 v250, 0x80, v250
	v_lshl_add_u32 v234, v250, 6, v177
	ds_read_b32 v234, v234
	v_add_u32_e32 v250, 0x244, v19
	v_min_u32_e32 v250, 0x80, v250
	v_lshl_add_u32 v235, v250, 6, v177
	ds_read_b32 v235, v235
	v_add_u32_e32 v250, 0x234, v19
	v_min_u32_e32 v250, 0x80, v250
	v_lshl_add_u32 v236, v250, 6, v177
	ds_read_b32 v236, v236
	v_add_u32_e32 v250, 0x224, v19
	v_min_u32_e32 v250, 0x80, v250
	v_lshl_add_u32 v237, v250, 6, v177
	ds_read_b32 v237, v237
	v_add_u32_e32 v250, 0x214, v19
	v_min_u32_e32 v250, 0x80, v250
	v_lshl_add_u32 v238, v250, 6, v177
	ds_read_b32 v238, v238
	v_add_u32_e32 v250, 0x204, v19
	v_min_u32_e32 v250, 0x80, v250
	v_lshl_add_u32 v239, v250, 6, v177
	ds_read_b32 v239, v239
	v_add_u32_e32 v250, 0x74, v19
	v_min_u32_e32 v250, 0x80, v250
	v_lshl_add_u32 v240, v250, 6, v177
	ds_read_b32 v240, v240
	v_add_u32_e32 v250, 0x64, v19
	v_min_u32_e32 v250, 0x80, v250
	v_lshl_add_u32 v241, v250, 6, v177
	ds_read_b32 v241, v241
	v_add_u32_e32 v250, 0x54, v19
	v_min_u32_e32 v250, 0x80, v250
	v_lshl_add_u32 v242, v250, 6, v177
	ds_read_b32 v242, v242
	v_add_u32_e32 v250, 0x44, v19
	v_min_u32_e32 v250, 0x80, v250
	v_lshl_add_u32 v243, v250, 6, v177
	ds_read_b32 v243, v243
	v_add_u32_e32 v250, 52, v19
	v_min_u32_e32 v250, 0x80, v250
	v_lshl_add_u32 v244, v250, 6, v177
	ds_read_b32 v244, v244
	v_add_u32_e32 v250, 36, v19
	v_min_u32_e32 v250, 0x80, v250
	v_lshl_add_u32 v245, v250, 6, v177
	ds_read_b32 v245, v245
	v_add_u32_e32 v250, 20, v19
	v_min_u32_e32 v250, 0x80, v250
	v_lshl_add_u32 v246, v250, 6, v177
	ds_read_b32 v246, v246
	v_add_u32_e32 v250, 4, v19
	v_min_u32_e32 v250, 0x80, v250
	v_lshl_add_u32 v247, v250, 6, v177
	ds_read_b32 v247, v247
	v_add_u32_e32 v248, 0x274, v19
	v_cmp_gt_u32_e32 vcc, 2.0, v248
	v_add_u32_e32 v249, 0x264, v19
	v_cmp_gt_u32_e64 s[10:11], 2.0, v249
	s_waitcnt lgkmcnt(15)
	v_add_f32_e32 v72, v84, v232
	v_cndmask_b32_e32 v72, v148, v72, vcc
	v_add_u32_e32 v248, 0x254, v19
	v_cmp_gt_u32_e32 vcc, 2.0, v248
	s_waitcnt lgkmcnt(14)
	v_add_f32_e32 v73, v85, v233
	v_cndmask_b32_e64 v73, v148, v73, s[10:11]
	v_add_u32_e32 v249, 0x244, v19
	v_cmp_gt_u32_e64 s[10:11], 2.0, v249
	s_waitcnt lgkmcnt(13)
	v_add_f32_e32 v74, v86, v234
	v_cndmask_b32_e32 v74, v148, v74, vcc
	v_add_u32_e32 v248, 0x234, v19
	v_cmp_gt_u32_e32 vcc, 2.0, v248
	s_waitcnt lgkmcnt(12)
	v_add_f32_e32 v75, v87, v235
	v_cndmask_b32_e64 v75, v148, v75, s[10:11]
	v_add_u32_e32 v249, 0x224, v19
	v_cmp_gt_u32_e64 s[10:11], 2.0, v249
	s_waitcnt lgkmcnt(11)
	v_add_f32_e32 v76, v68, v236
	v_cndmask_b32_e32 v76, v148, v76, vcc
	v_add_u32_e32 v248, 0x214, v19
	v_cmp_gt_u32_e32 vcc, 2.0, v248
	s_waitcnt lgkmcnt(10)
	v_add_f32_e32 v77, v69, v237
	v_cndmask_b32_e64 v77, v148, v77, s[10:11]
	v_add_u32_e32 v249, 0x204, v19
	v_cmp_gt_u32_e64 s[10:11], 2.0, v249
	s_waitcnt lgkmcnt(9)
	v_add_f32_e32 v68, v70, v238
	v_cndmask_b32_e32 v68, v148, v68, vcc
	v_add_u32_e32 v248, 0x74, v19
	v_cmp_gt_u32_e32 vcc, 2.0, v248
	s_waitcnt lgkmcnt(8)
	v_add_f32_e32 v69, v71, v239
	v_cndmask_b32_e64 v69, v148, v69, s[10:11]
	v_add_u32_e32 v249, 0x64, v19
	v_cmp_gt_u32_e64 s[10:11], 2.0, v249
	s_waitcnt lgkmcnt(7)
	v_add_f32_e32 v70, v64, v240
	v_cndmask_b32_e32 v70, v148, v70, vcc
	v_add_u32_e32 v248, 0x54, v19
	v_cmp_gt_u32_e32 vcc, 2.0, v248
	s_waitcnt lgkmcnt(6)
	v_add_f32_e32 v71, v65, v241
	v_cndmask_b32_e64 v71, v148, v71, s[10:11]
	v_add_u32_e32 v249, 0x44, v19
	v_cmp_gt_u32_e64 s[10:11], 2.0, v249
	s_waitcnt lgkmcnt(5)
	v_add_f32_e32 v64, v66, v242
	v_cndmask_b32_e32 v64, v148, v64, vcc
	v_add_u32_e32 v248, 52, v19
	v_cmp_gt_u32_e32 vcc, 2.0, v248
	s_waitcnt lgkmcnt(4)
	v_add_f32_e32 v65, v67, v243
	v_cndmask_b32_e64 v65, v148, v65, s[10:11]
	v_add_u32_e32 v249, 36, v19
	v_cmp_gt_u32_e64 s[10:11], 2.0, v249
	s_waitcnt lgkmcnt(3)
	v_add_f32_e32 v66, v60, v244
	v_cndmask_b32_e32 v66, v148, v66, vcc
	v_add_u32_e32 v248, 20, v19
	v_cmp_gt_u32_e32 vcc, 2.0, v248
	s_waitcnt lgkmcnt(2)
	v_add_f32_e32 v67, v61, v245
	v_cndmask_b32_e64 v67, v148, v67, s[10:11]
	v_add_u32_e32 v249, 4, v19
	v_cmp_gt_u32_e64 s[10:11], 2.0, v249
	s_waitcnt lgkmcnt(1)
	v_add_f32_e32 v60, v62, v246
	v_cndmask_b32_e32 v60, v148, v60, vcc
	s_waitcnt lgkmcnt(0)
	v_add_f32_e32 v61, v63, v247
	v_cndmask_b32_e64 v61, v148, v61, s[10:11]
	v_pk_add_f32 v[104:105], v[72:73], v[114:115] neg_lo:[0,1] neg_hi:[0,1]
	v_pk_add_f32 v[106:107], v[74:75], v[114:115] neg_lo:[0,1] neg_hi:[0,1]
	v_pk_add_f32 v[100:101], v[76:77], v[114:115] neg_lo:[0,1] neg_hi:[0,1]
	v_pk_add_f32 v[102:103], v[68:69], v[114:115] neg_lo:[0,1] neg_hi:[0,1]
	v_pk_add_f32 v[96:97], v[70:71], v[114:115] neg_lo:[0,1] neg_hi:[0,1]
	v_pk_add_f32 v[98:99], v[64:65], v[114:115] neg_lo:[0,1] neg_hi:[0,1]
	v_pk_add_f32 v[92:93], v[66:67], v[114:115] neg_lo:[0,1] neg_hi:[0,1]
	v_pk_add_f32 v[94:95], v[60:61], v[114:115] neg_lo:[0,1] neg_hi:[0,1]
